# retention core: EL broadcast from register, att and Qd*S stages merged into one pipelined LDS/MFMA loop, att*V tails merged, V load hoisted to loop top
# speedup vs baseline: 1.0087x; 1.0063x over previous
; #define LAS __attribute__((address_space(3)))
; __device__ __forceinline__ bf16_t f2bf(float x) { return (bf16_t)(cvt_pk_bf16(x, x) & 0xffffu); }
; #define GLA_BAR() do { asm volatile("s_waitcnt lgkmcnt(0)" ::: "memory"); __builtin_amdgcn_s_barrier(); asm volatile("" ::: "memory"); } while (0)
; template <int DK, int DVS, bool RET> ...
;     ...
;             const int tcs = (wid & 1) * 2;
;             f32x4 a0 = {0.f, 0.f, 0.f, 0.f}, a1 = {0.f, 0.f, 0.f, 0.f};
; #pragma unroll
;             for (int kk = 0; kk < DK / 32; ++kk) {
;                 const bf16x8 af = *(const LAS bf16x8*)(QD + (tr * 16 + l16) * LK + kk * 32 + quad * 8);
;                 const bf16x8 b0 = *(const LAS bf16x8*)(KD + (tcs * 16 + l16) * LK + kk * 32 + quad * 8);
;                 const bf16x8 b1 = *(const LAS bf16x8*)(KD + ((tcs + 1) * 16 + l16) * LK + kk * 32 + quad * 8);
;                 a0 = __builtin_amdgcn_mfma_f32_16x16x32_bf16(af, b0, a0, 0, 0, 0);
;                 a1 = __builtin_amdgcn_mfma_f32_16x16x32_bf16(af, b1, a1, 0, 0, 0);
;                 asm volatile("" ::: "memory");
;             }
; #pragma unroll
;             for (int j = 0; j < 4; ++j) { const int p = tr * 16 + quad * 4 + j, s0 = tcs * 16 + l16, s1 = s0 + 16;
;                 AT[p * LS + s0] = f2bf((s0 <= p) ? a0[j] : 0.f); AT[p * LS + s1] = f2bf((s1 <= p) ? a1[j] : 0.f); }
;         }
;         GLA_BAR();
; #pragma unroll
;         for (int t = 0; t < NOT; ++t) { const int tc = (wid & 1) * NOT + t; f32x4 acc = {0.f, 0.f, 0.f, 0.f};
; #pragma unroll
;             for (int kk = 0; kk < DK / 32; ++kk) {
;                 const bf16x8 af = *(const LAS bf16x8*)(QD + (tr * 16 + l16) * LK + kk * 32 + quad * 8);
;                 const bf16x8 bf = *(const LAS bf16x8*)(STB + (tc * 16 + l16) * LK + kk * 32 + quad * 8);
;                 acc = __builtin_amdgcn_mfma_f32_16x16x32_bf16(af, bf, acc, 0, 0, 0);
;                 if ((kk & 3) == 3) asm volatile("" ::: "memory"); }
.LBB0_70:
	s_waitcnt lgkmcnt(0)
	s_barrier
	v_add_u32_e32 v198, v175, v123
	ds_read_b128 v[232:235], v218
	ds_read_b128 v[236:239], v174
	ds_read_b128 v[240:243], v174 offset:8448
	ds_read_b128 v[244:247], v198
	ds_read_b128 v[248:251], v219
	s_waitcnt lgkmcnt(3)
	v_mfma_f32_16x16x32_bf16 v[228:231], v[232:235], v[236:239], 0
	ds_read_b128 v[212:215], v218 offset:64
	ds_read_b128 v[236:239], v174 offset:64
	s_waitcnt lgkmcnt(4)
	v_mfma_f32_16x16x32_bf16 v[64:67], v[232:235], v[240:243], 0
	ds_read_b128 v[240:243], v174 offset:8512
	s_waitcnt lgkmcnt(4)
	v_mfma_f32_16x16x32_bf16 v[220:223], v[232:235], v[244:247], 0
	ds_read_b128 v[244:247], v198 offset:64
	s_waitcnt lgkmcnt(4)
	v_mfma_f32_16x16x32_bf16 v[224:227], v[232:235], v[248:251], 0
	ds_read_b128 v[248:251], v219 offset:64
	s_waitcnt lgkmcnt(3)
	v_mfma_f32_16x16x32_bf16 v[228:231], v[212:215], v[236:239], v[228:231]
	ds_read_b128 v[232:235], v218 offset:128
	ds_read_b128 v[236:239], v174 offset:128
	s_waitcnt lgkmcnt(4)
	v_mfma_f32_16x16x32_bf16 v[64:67], v[212:215], v[240:243], v[64:67]
	ds_read_b128 v[240:243], v174 offset:8576
	s_waitcnt lgkmcnt(4)
	v_mfma_f32_16x16x32_bf16 v[220:223], v[212:215], v[244:247], v[220:223]
	ds_read_b128 v[244:247], v198 offset:128
	s_waitcnt lgkmcnt(4)
	v_mfma_f32_16x16x32_bf16 v[224:227], v[212:215], v[248:251], v[224:227]
	ds_read_b128 v[248:251], v219 offset:128
	s_waitcnt lgkmcnt(3)
	v_mfma_f32_16x16x32_bf16 v[228:231], v[232:235], v[236:239], v[228:231]
	ds_read_b128 v[212:215], v218 offset:192
	ds_read_b128 v[236:239], v174 offset:192
	s_waitcnt lgkmcnt(4)
	v_mfma_f32_16x16x32_bf16 v[64:67], v[232:235], v[240:243], v[64:67]
	ds_read_b128 v[240:243], v174 offset:8640
	s_waitcnt lgkmcnt(4)
	v_mfma_f32_16x16x32_bf16 v[220:223], v[232:235], v[244:247], v[220:223]
	ds_read_b128 v[244:247], v198 offset:192
	s_waitcnt lgkmcnt(4)
	v_mfma_f32_16x16x32_bf16 v[224:227], v[232:235], v[248:251], v[224:227]
	ds_read_b128 v[248:251], v219 offset:192
	s_waitcnt lgkmcnt(3)
	v_mfma_f32_16x16x32_bf16 v[228:231], v[212:215], v[236:239], v[228:231]
	ds_read_b128 v[232:235], v218 offset:256
	ds_read_b128 v[236:239], v174 offset:256
	s_waitcnt lgkmcnt(4)
	v_mfma_f32_16x16x32_bf16 v[64:67], v[212:215], v[240:243], v[64:67]
	ds_read_b128 v[240:243], v174 offset:8704
	s_waitcnt lgkmcnt(4)
	v_mfma_f32_16x16x32_bf16 v[220:223], v[212:215], v[244:247], v[220:223]
	ds_read_b128 v[244:247], v198 offset:256
	s_waitcnt lgkmcnt(4)
	v_mfma_f32_16x16x32_bf16 v[224:227], v[212:215], v[248:251], v[224:227]
	ds_read_b128 v[248:251], v219 offset:256
	s_waitcnt lgkmcnt(3)
	v_mfma_f32_16x16x32_bf16 v[228:231], v[232:235], v[236:239], v[228:231]
	ds_read_b128 v[212:215], v218 offset:320
	ds_read_b128 v[236:239], v174 offset:320
	s_waitcnt lgkmcnt(4)
	v_mfma_f32_16x16x32_bf16 v[64:67], v[232:235], v[240:243], v[64:67]
	ds_read_b128 v[240:243], v174 offset:8768
	s_waitcnt lgkmcnt(4)
	v_mfma_f32_16x16x32_bf16 v[220:223], v[232:235], v[244:247], v[220:223]
	ds_read_b128 v[244:247], v198 offset:320
	s_waitcnt lgkmcnt(4)
	v_mfma_f32_16x16x32_bf16 v[224:227], v[232:235], v[248:251], v[224:227]
	ds_read_b128 v[248:251], v219 offset:320
	s_waitcnt lgkmcnt(3)
	v_mfma_f32_16x16x32_bf16 v[228:231], v[212:215], v[236:239], v[228:231]
	ds_read_b128 v[232:235], v218 offset:384
	ds_read_b128 v[236:239], v174 offset:384
	s_waitcnt lgkmcnt(4)
	v_mfma_f32_16x16x32_bf16 v[64:67], v[212:215], v[240:243], v[64:67]
	ds_read_b128 v[240:243], v174 offset:8832
	s_waitcnt lgkmcnt(4)
	v_mfma_f32_16x16x32_bf16 v[220:223], v[212:215], v[244:247], v[220:223]
	ds_read_b128 v[244:247], v198 offset:384
	s_waitcnt lgkmcnt(4)
	v_mfma_f32_16x16x32_bf16 v[224:227], v[212:215], v[248:251], v[224:227]
	ds_read_b128 v[248:251], v219 offset:384
	s_waitcnt lgkmcnt(3)
	v_mfma_f32_16x16x32_bf16 v[228:231], v[232:235], v[236:239], v[228:231]
	ds_read_b128 v[212:215], v218 offset:448
	ds_read_b128 v[236:239], v174 offset:448
	s_waitcnt lgkmcnt(4)
	v_mfma_f32_16x16x32_bf16 v[64:67], v[232:235], v[240:243], v[64:67]
	ds_read_b128 v[240:243], v174 offset:8896
	s_waitcnt lgkmcnt(4)
	v_mfma_f32_16x16x32_bf16 v[220:223], v[232:235], v[244:247], v[220:223]
	ds_read_b128 v[244:247], v198 offset:448
	s_waitcnt lgkmcnt(4)
	v_mfma_f32_16x16x32_bf16 v[224:227], v[232:235], v[248:251], v[224:227]
	ds_read_b128 v[248:251], v219 offset:448
	s_waitcnt lgkmcnt(3)
	v_mfma_f32_16x16x32_bf16 v[228:231], v[212:215], v[236:239], v[228:231]
	s_waitcnt lgkmcnt(2)
	v_mfma_f32_16x16x32_bf16 v[64:67], v[212:215], v[240:243], v[64:67]
	s_waitcnt lgkmcnt(1)
	v_mfma_f32_16x16x32_bf16 v[220:223], v[212:215], v[244:247], v[220:223]
	s_waitcnt lgkmcnt(0)
	v_mfma_f32_16x16x32_bf16 v[224:227], v[212:215], v[248:251], v[224:227]
	s_nop 6
	v_cvt_pk_bf16_f32 v64, v64, s0
	v_cndmask_b32_e64 v64, v64, 0, s[8:9]
	ds_write_b16 v199, v64 offset:32
	v_cvt_pk_bf16_f32 v64, v229, s0
	v_cndmask_b32_e64 v64, v64, 0, s[10:11]
	ds_write_b16 v200, v64
	v_cvt_pk_bf16_f32 v64, v65, s0
	v_cndmask_b32_e64 v64, v64, 0, s[12:13]
	ds_write_b16 v200, v64 offset:32
	v_cvt_pk_bf16_f32 v64, v230, s0
	v_cndmask_b32_e64 v64, v64, 0, s[14:15]
	ds_write_b16 v201, v64
	v_cvt_pk_bf16_f32 v64, v66, s0
	v_cndmask_b32_e64 v64, v64, 0, s[16:17]
	ds_write_b16 v201, v64 offset:32
	v_cvt_pk_bf16_f32 v64, v231, s0
	v_cndmask_b32_e64 v64, v64, 0, s[18:19]
	v_cvt_pk_bf16_f32 v198, v228, s0
	ds_write_b16 v202, v64
	v_cvt_pk_bf16_f32 v64, v67, s0
	v_cndmask_b32_e64 v198, v198, 0, s[6:7]
	v_cndmask_b32_e64 v64, v64, 0, s[20:21]
	ds_write_b16 v199, v198
	ds_write_b16 v202, v64 offset:32
	s_waitcnt lgkmcnt(0)
	s_barrier
; #define LAS __attribute__((address_space(3)))
; #define GAS __attribute__((address_space(1)))
; __device__ __forceinline__ bf16_t f2bf(float x) { return (bf16_t)(cvt_pk_bf16(x, x) & 0xffffu); }
; #define TRR(dst, base, OFF) asm volatile("ds_read_b64_tr_b16 %0, %1 offset:%2" : "=&v"(dst) : "v"(base), "i"(OFF) : "memory")
; template <int DK, int DVS, bool RET> ...
;     ...
;             { s16x4 v00, v01, v10, v11; const int vb = vtr + tc * 32;
;                 TRR(v00, vb, 0); TRR(v01, vb, 4 * LV * 2); TRR(v10, vb, 32 * LV * 2); TRR(v11, vb, 36 * LV * 2);
;                 const bf16x8 a0 = *(const LAS bf16x8*)(AT + (tr * 16 + l16) * LS + quad * 8), a1 = *(const LAS bf16x8*)(AT + (tr * 16 + l16) * LS + 32 + quad * 8);
;                 asm volatile("s_waitcnt lgkmcnt(0)" ::: "memory"); __builtin_amdgcn_sched_barrier(0);
;                 acc = __builtin_amdgcn_mfma_f32_16x16x32_bf16(a0, TRFRAG(v00, v01), acc, 0, 0, 0);
;                 acc = __builtin_amdgcn_mfma_f32_16x16x32_bf16(a1, TRFRAG(v10, v11), acc, 0, 0, 0); }
; #pragma unroll
;             for (int j = 0; j < 4; ++j) { const int p = tr * 16 + quad * 4 + j; const long row = R0 + (dir ? 63 - p : p);
;                 ((GAS bf16_t*)Od)[row * ldv + vcol0 + tc * 16 + l16] = f2bf(acc[j]); }
;         }
;         { s16x4 a00, a01, a10, a11; const int vb = vtr + tv * 32;
;             TRR(a00, vb, 0); TRR(a01, vb, 4 * LV * 2); TRR(a10, vb, 32 * LV * 2); TRR(a11, vb, 36 * LV * 2);
; #pragma unroll
;             for (int t0 = 0; t0 < TPW; t0 += 2) {
;                 s16x4 b[2][4];
; #pragma unroll
;                 for (int u = 0; u < 2; ++u) { const int kb = ktr + (kt0 + t0 + u) * 32;
;                     TRR(b[u][0], kb, 0); TRR(b[u][1], kb, 4 * LK * 2); TRR(b[u][2], kb, 32 * LK * 2); TRR(b[u][3], kb, 36 * LK * 2); }
;                 asm volatile("s_waitcnt lgkmcnt(0)" ::: "memory"); __builtin_amdgcn_sched_barrier(0);
; #pragma unroll
;                 for (int u = 0; u < 2; ++u) { const int t = t0 + u;
;                     st[t] = __builtin_amdgcn_mfma_f32_16x16x32_bf16(TRFRAG(a00, a01), TRFRAG(b[u][0], b[u][1]), st[t], 0, 0, 0);
;                     st[t] = __builtin_amdgcn_mfma_f32_16x16x32_bf16(TRFRAG(a10, a11), TRFRAG(b[u][2], b[u][3]), st[t], 0, 0, 0); }
;             }
; #pragma unroll
;             for (int t = 0; t < TPW; ++t) st[t] = st[t] * EL[(kt0 + t) * 16 + l16];
	ds_read_b128 v[248:251], v176
	ds_read_b128 v[212:215], v176 offset:64
	ds_read_b64_tr_b16 v[232:233], v203 offset:0
	ds_read_b64_tr_b16 v[234:235], v203 offset:0x240
	ds_read_b64_tr_b16 v[236:237], v203 offset:0x1200
	ds_read_b64_tr_b16 v[238:239], v203 offset:0x1440
	ds_read_b64_tr_b16 v[240:241], v177 offset:0
	ds_read_b64_tr_b16 v[242:243], v177 offset:0x240
	ds_read_b64_tr_b16 v[244:245], v177 offset:0x1200
	ds_read_b64_tr_b16 v[246:247], v177 offset:0x1440
	s_waitcnt lgkmcnt(6)
	v_mfma_f32_16x16x32_bf16 v[220:223], v[248:251], v[232:235], v[220:223]
	s_waitcnt lgkmcnt(4)
	v_mfma_f32_16x16x32_bf16 v[220:223], v[212:215], v[236:239], v[220:223]
	s_waitcnt lgkmcnt(2)
	v_mfma_f32_16x16x32_bf16 v[224:227], v[248:251], v[240:243], v[224:227]
	s_waitcnt lgkmcnt(0)
	v_mfma_f32_16x16x32_bf16 v[224:227], v[212:215], v[244:247], v[224:227]
	v_lshl_add_u64 v[232:233], s[30:31], 0, v[104:105]
	v_lshlrev_b64 v[232:233], 12, v[232:233]
	v_lshl_add_u64 v[234:235], s[30:31], 0, v[108:109]
	v_lshlrev_b64 v[234:235], 12, v[234:235]
	v_lshl_add_u64 v[236:237], s[30:31], 0, v[110:111]
	v_lshlrev_b64 v[236:237], 12, v[236:237]
	v_lshl_add_u64 v[238:239], s[30:31], 0, v[112:113]
	v_lshlrev_b64 v[238:239], 12, v[238:239]
	s_nop 1
	v_cvt_pk_bf16_f32 v198, v220, s0
	v_lshl_add_u64 v[240:241], v[106:107], 0, v[232:233]
	global_store_short v[240:241], v198, off
	v_cvt_pk_bf16_f32 v242, v221, s0
	v_lshl_add_u64 v[244:245], v[106:107], 0, v[234:235]
	global_store_short v[244:245], v242, off
	v_cvt_pk_bf16_f32 v198, v222, s0
	v_lshl_add_u64 v[240:241], v[106:107], 0, v[236:237]
	global_store_short v[240:241], v198, off
	v_cvt_pk_bf16_f32 v242, v223, s0
	v_lshl_add_u64 v[244:245], v[106:107], 0, v[238:239]
	global_store_short v[244:245], v242, off
	s_nop 3
	v_cvt_pk_bf16_f32 v198, v224, s0
	v_lshl_add_u64 v[240:241], v[114:115], 0, v[232:233]
	global_store_short v[240:241], v198, off
	v_cvt_pk_bf16_f32 v242, v225, s0
	v_lshl_add_u64 v[244:245], v[114:115], 0, v[234:235]
	global_store_short v[244:245], v242, off
	v_cvt_pk_bf16_f32 v198, v226, s0
	v_lshl_add_u64 v[240:241], v[114:115], 0, v[236:237]
	global_store_short v[240:241], v198, off
	v_cvt_pk_bf16_f32 v242, v227, s0
	v_lshl_add_u64 v[244:245], v[114:115], 0, v[238:239]
	global_store_short v[244:245], v242, off
	ds_read_b64_tr_b16 v[64:65], v144 offset:0
	ds_read_b64_tr_b16 v[66:67], v144 offset:0x240
	ds_read_b64_tr_b16 v[228:229], v144 offset:0x1200
	ds_read_b64_tr_b16 v[230:231], v144 offset:0x1440
	ds_read_b64_tr_b16 v[232:233], v83 offset:0
	ds_read_b64_tr_b16 v[234:235], v83 offset:0x840
	ds_read_b64_tr_b16 v[236:237], v83 offset:0x4200
	ds_read_b64_tr_b16 v[238:239], v83 offset:0x4a40
	ds_read_b64_tr_b16 v[240:241], v85 offset:0
	ds_read_b64_tr_b16 v[242:243], v85 offset:0x840
	ds_read_b64_tr_b16 v[244:245], v85 offset:0x4200
	ds_read_b64_tr_b16 v[246:247], v85 offset:0x4a40
	s_waitcnt lgkmcnt(0)
	s_nop 0
	v_mfma_f32_16x16x32_bf16 v[56:59], v[64:67], v[232:235], v[56:59]
	ds_read_b64_tr_b16 v[232:233], v204 offset:0
	ds_read_b64_tr_b16 v[234:235], v204 offset:0x840
	v_mfma_f32_16x16x32_bf16 v[56:59], v[228:231], v[236:239], v[56:59]
	ds_read_b64_tr_b16 v[236:237], v204 offset:0x4200
	ds_read_b64_tr_b16 v[238:239], v204 offset:0x4a40
	v_mfma_f32_16x16x32_bf16 v[60:63], v[64:67], v[240:243], v[60:63]
	ds_read_b64_tr_b16 v[240:241], v205 offset:0
	ds_read_b64_tr_b16 v[242:243], v205 offset:0x840
	v_mfma_f32_16x16x32_bf16 v[60:63], v[228:231], v[244:247], v[60:63]
	ds_read_b64_tr_b16 v[244:245], v205 offset:0x4200
	ds_read_b64_tr_b16 v[246:247], v205 offset:0x4a40
	s_waitcnt lgkmcnt(0)
	v_mfma_f32_16x16x32_bf16 v[48:51], v[64:67], v[232:235], v[48:51]
	ds_read_b64_tr_b16 v[232:233], v206 offset:0
	ds_read_b64_tr_b16 v[234:235], v206 offset:0x840
	v_mfma_f32_16x16x32_bf16 v[48:51], v[228:231], v[236:239], v[48:51]
	ds_read_b64_tr_b16 v[236:237], v206 offset:0x4200
	ds_read_b64_tr_b16 v[238:239], v206 offset:0x4a40
	v_mfma_f32_16x16x32_bf16 v[52:55], v[64:67], v[240:243], v[52:55]
	ds_read_b64_tr_b16 v[240:241], v207 offset:0
	ds_read_b64_tr_b16 v[242:243], v207 offset:0x840
	v_mfma_f32_16x16x32_bf16 v[52:55], v[228:231], v[244:247], v[52:55]
	ds_read_b64_tr_b16 v[244:245], v207 offset:0x4200
	ds_read_b64_tr_b16 v[246:247], v207 offset:0x4a40
	s_waitcnt lgkmcnt(0)
	v_mfma_f32_16x16x32_bf16 v[40:43], v[64:67], v[232:235], v[40:43]
	ds_read_b64_tr_b16 v[232:233], v208 offset:0
	ds_read_b64_tr_b16 v[234:235], v208 offset:0x840
	v_mfma_f32_16x16x32_bf16 v[40:43], v[228:231], v[236:239], v[40:43]
	ds_read_b64_tr_b16 v[236:237], v208 offset:0x4200
	ds_read_b64_tr_b16 v[238:239], v208 offset:0x4a40
	v_mfma_f32_16x16x32_bf16 v[44:47], v[64:67], v[240:243], v[44:47]
	ds_read_b64_tr_b16 v[240:241], v209 offset:0
	ds_read_b64_tr_b16 v[242:243], v209 offset:0x840
	v_mfma_f32_16x16x32_bf16 v[44:47], v[228:231], v[244:247], v[44:47]
	ds_read_b64_tr_b16 v[244:245], v209 offset:0x4200
	ds_read_b64_tr_b16 v[246:247], v209 offset:0x4a40
	s_waitcnt lgkmcnt(0)
	v_mfma_f32_16x16x32_bf16 v[36:39], v[64:67], v[232:235], v[36:39]
	s_add_i32 s42, s42, -1
	s_cmpk_lg_i32 s42, 0xffbc
	s_mov_b32 s45, s36
	v_mfma_f32_16x16x32_bf16 v[0:3], v[64:67], v[240:243], v[0:3]
	v_mov_b32_e32 v64, v173
	v_mfma_f32_16x16x32_bf16 v[36:39], v[228:231], v[236:239], v[36:39]
	v_mfma_f32_16x16x32_bf16 v[0:3], v[228:231], v[244:247], v[0:3]
	v_pk_mul_f32 v[58:59], v[58:59], v[64:65] op_sel_hi:[1,0]
	v_pk_mul_f32 v[56:57], v[56:57], v[64:65] op_sel_hi:[1,0]
	v_pk_mul_f32 v[62:63], v[62:63], v[64:65] op_sel_hi:[1,0]
	v_pk_mul_f32 v[60:61], v[60:61], v[64:65] op_sel_hi:[1,0]
	v_pk_mul_f32 v[50:51], v[50:51], v[64:65] op_sel_hi:[1,0]
	v_pk_mul_f32 v[48:49], v[48:49], v[64:65] op_sel_hi:[1,0]
	v_pk_mul_f32 v[54:55], v[54:55], v[64:65] op_sel_hi:[1,0]
	v_pk_mul_f32 v[52:53], v[52:53], v[64:65] op_sel_hi:[1,0]
	v_pk_mul_f32 v[42:43], v[42:43], v[64:65] op_sel_hi:[1,0]
	v_pk_mul_f32 v[40:41], v[40:41], v[64:65] op_sel_hi:[1,0]
	v_pk_mul_f32 v[46:47], v[46:47], v[64:65] op_sel_hi:[1,0]
	v_pk_mul_f32 v[44:45], v[44:45], v[64:65] op_sel_hi:[1,0]
	v_pk_mul_f32 v[38:39], v[38:39], v[64:65] op_sel_hi:[1,0]
	v_pk_mul_f32 v[36:37], v[36:37], v[64:65] op_sel_hi:[1,0]
	v_pk_mul_f32 v[2:3], v[2:3], v[64:65] op_sel_hi:[1,0]
	v_pk_mul_f32 v[0:1], v[0:1], v[64:65] op_sel_hi:[1,0]
	s_cbranch_scc0 .LBB0_68
; #define LAS __attribute__((address_space(3)))
; #define GAS __attribute__((address_space(1)))
; __device__ __forceinline__ bf16_t f2bf(float x) { return (bf16_t)(cvt_pk_bf16(x, x) & 0xffffu); }
; __device__ __forceinline__ float bf2f(bf16_t v) { return __uint_as_float((unsigned)v << 16); }
; __device__ __forceinline__ u32x4 pack8(const float* v) { u32x4 w; w.x = cvt_pk_bf16(v[0], v[1]); w.y = cvt_pk_bf16(v[2], v[3]); w.z = cvt_pk_bf16(v[4], v[5]); w.w = cvt_pk_bf16(v[6], v[7]); return w; }
; #define GLA_BAR() do { asm volatile("s_waitcnt lgkmcnt(0)" ::: "memory"); __builtin_amdgcn_s_barrier(); asm volatile("" ::: "memory"); } while (0)
; template <int DK, int DVS, bool RET> ...
;     ...
;         GLA_BAR();
;         {
; #pragma unroll
;             for (int t = 0; t < TPW; ++t)
; #pragma unroll
;                 for (int j = 0; j < 4; ++j) STB[(tv * 16 + quad * 4 + j) * LK + (kt0 + t) * 16 + l16] = f2bf(st[t][j]);
;             { const int p = tid >> 3, vg = tid & 7; const long row = R0 + (dir ? 63 - p : p); vraw = *(const GAS vvec_t*)(Vg + row * ldv + vcol0 + vg * VPT); }
;             float bl;
;             if constexpr (RET) {
;                 static_assert(!RET || DK == 256, "retention prep: 64 x 256 = 2048 eight-wide items, four per thread");
;                 bl = 64.f * lg;
; #pragma unroll
;                 for (int j = 0; j < 4; ++j) { const int it = tid + 512 * j, p = it & 63, k0 = (it >> 6) * 8; const float bb = (float)(p + 1) * lg;
;                     const float eq = __expf(bb), ek = __expf(-bb); float a[8], c[8];
; #pragma unroll
;                     for (int e = 0; e < 8; ++e) { a[e] = bf2f((bf16_t)qv[j][e]) * eq; c[e] = bf2f((bf16_t)kv[j][e]) * ek; }
;                     *(LAS u32x4*)(QD + p * LK + k0) = pack8(a); *(LAS u32x4*)(KD + p * LK + k0) = pack8(c); }
.LBB0_71:
	v_cvt_pk_bf16_f32 v64, v56, s0
	s_cmp_gt_u32 s45, 3
	s_cselect_b32 s30, 0x47, 3
	s_add_i32 s36, s30, s42
	s_and_b64 s[30:31], s[22:23], exec
	s_cselect_b32 s30, s45, s36
	s_lshl_b32 s30, s30, 6
	s_ashr_i32 s31, s30, 31
	s_add_u32 s30, s44, s30
	s_addc_u32 s31, s43, s31
	v_lshl_add_u64 v[214:215], s[30:31], 0, v[96:97]
	v_lshlrev_b64 v[214:215], 12, v[214:215]
	v_lshl_add_u64 v[214:215], v[98:99], 0, v[214:215]
	global_load_dwordx4 v[212:215], v[214:215], off
	s_waitcnt lgkmcnt(0)
	s_barrier
	ds_write_b16 v210, v64
	v_cvt_pk_bf16_f32 v64, v57, s0
	ds_write_b16 v210, v64 offset:528
	v_cvt_pk_bf16_f32 v64, v58, s0
	ds_write_b16 v210, v64 offset:1056
	v_cvt_pk_bf16_f32 v64, v59, s0
	ds_write_b16 v210, v64 offset:1584
	v_cvt_pk_bf16_f32 v64, v60, s0
	ds_write_b16 v210, v64 offset:32
	v_cvt_pk_bf16_f32 v64, v61, s0
	ds_write_b16 v210, v64 offset:560
	v_cvt_pk_bf16_f32 v64, v62, s0
	ds_write_b16 v210, v64 offset:1088
	v_cvt_pk_bf16_f32 v64, v63, s0
	ds_write_b16 v210, v64 offset:1616
	v_cvt_pk_bf16_f32 v64, v48, s0
	ds_write_b16 v210, v64 offset:64
	v_cvt_pk_bf16_f32 v64, v49, s0
	ds_write_b16 v210, v64 offset:592
	v_cvt_pk_bf16_f32 v64, v50, s0
	ds_write_b16 v210, v64 offset:1120
	v_cvt_pk_bf16_f32 v64, v51, s0
	ds_write_b16 v210, v64 offset:1648
	v_cvt_pk_bf16_f32 v64, v52, s0
	ds_write_b16 v210, v64 offset:96
	v_cvt_pk_bf16_f32 v64, v53, s0
	ds_write_b16 v210, v64 offset:624
	v_cvt_pk_bf16_f32 v64, v54, s0
	ds_write_b16 v210, v64 offset:1152
	v_cvt_pk_bf16_f32 v64, v55, s0
	ds_write_b16 v210, v64 offset:1680
	v_cvt_pk_bf16_f32 v64, v40, s0
	ds_write_b16 v210, v64 offset:128
	v_cvt_pk_bf16_f32 v64, v41, s0
	ds_write_b16 v210, v64 offset:656
	v_cvt_pk_bf16_f32 v64, v42, s0
	ds_write_b16 v210, v64 offset:1184
	v_cvt_pk_bf16_f32 v64, v43, s0
	ds_write_b16 v210, v64 offset:1712
	v_cvt_pk_bf16_f32 v64, v44, s0
	ds_write_b16 v210, v64 offset:160
	v_cvt_pk_bf16_f32 v64, v45, s0
	ds_write_b16 v210, v64 offset:688
	v_cvt_pk_bf16_f32 v64, v46, s0
	s_cmp_gt_u32 s45, 3
	ds_write_b16 v210, v64 offset:1216
	v_cvt_pk_bf16_f32 v64, v47, s0
	s_cselect_b32 s30, 0x47, 3
	ds_write_b16 v210, v64 offset:1744
	v_cvt_pk_bf16_f32 v64, v36, s0
	s_add_i32 s36, s30, s42
	ds_write_b16 v210, v64 offset:192
	v_cvt_pk_bf16_f32 v64, v37, s0
	s_and_b64 s[30:31], s[22:23], exec
	ds_write_b16 v210, v64 offset:720
	v_cvt_pk_bf16_f32 v64, v38, s0
	s_cselect_b32 s30, s45, s36
	ds_write_b16 v210, v64 offset:1248
	v_cvt_pk_bf16_f32 v64, v39, s0
	s_lshl_b32 s30, s30, 6
	ds_write_b16 v210, v64 offset:1776
	v_cvt_pk_bf16_f32 v64, v0, s0
	s_ashr_i32 s31, s30, 31
	ds_write_b16 v210, v64 offset:224
	v_cvt_pk_bf16_f32 v64, v1, s0
	ds_write_b16 v210, v64 offset:752
	v_cvt_pk_bf16_f32 v64, v2, s0
	s_add_u32 s30, s44, s30
	ds_write_b16 v210, v64 offset:1280
	v_cvt_pk_bf16_f32 v64, v3, s0
	s_addc_u32 s31, s43, s31
	ds_write_b16 v210, v64 offset:1808
	s_waitcnt vmcnt(7)
	v_and_b32_e32 v231, 0xffff0000, v8
	v_lshlrev_b32_e32 v230, 16, v8
	v_and_b32_e32 v229, 0xffff0000, v4
	v_lshlrev_b32_e32 v228, 16, v4
	v_pk_mul_f32 v[232:233], v[102:103], v[230:231]
	v_and_b32_e32 v231, 0xffff0000, v5
	v_lshlrev_b32_e32 v230, 16, v5
	v_and_b32_e32 v237, 0xffff0000, v6
	v_lshlrev_b32_e32 v236, 16, v6
	v_and_b32_e32 v241, 0xffff0000, v7
	v_lshlrev_b32_e32 v240, 16, v7
	v_pk_mul_f32 v[228:229], v[100:101], v[228:229]
	v_pk_mul_f32 v[230:231], v[100:101], v[230:231]
	v_and_b32_e32 v235, 0xffff0000, v9
	v_lshlrev_b32_e32 v234, 16, v9
	v_pk_mul_f32 v[236:237], v[100:101], v[236:237]
	v_and_b32_e32 v239, 0xffff0000, v10
	v_lshlrev_b32_e32 v238, 16, v10
	v_pk_mul_f32 v[240:241], v[100:101], v[240:241]
	v_and_b32_e32 v243, 0xffff0000, v11
	v_lshlrev_b32_e32 v242, 16, v11
	v_pk_mul_f32 v[234:235], v[102:103], v[234:235]
	v_pk_mul_f32 v[238:239], v[102:103], v[238:239]
	v_pk_mul_f32 v[242:243], v[102:103], v[242:243]
	v_cvt_pk_bf16_f32 v228, v228, v229
	v_cvt_pk_bf16_f32 v229, v230, v231
	v_cvt_pk_bf16_f32 v230, v236, v237
	v_cvt_pk_bf16_f32 v231, v240, v241
	ds_write_b128 v178, v[228:231]
	v_cvt_pk_bf16_f32 v228, v232, v233
	v_cvt_pk_bf16_f32 v229, v234, v235
	v_cvt_pk_bf16_f32 v230, v238, v239
	v_cvt_pk_bf16_f32 v231, v242, v243
	ds_write_b128 v179, v[228:231]
	s_waitcnt vmcnt(5)
; #define LAS __attribute__((address_space(3)))
; __device__ __forceinline__ bf16_t f2bf(float x) { return (bf16_t)(cvt_pk_bf16(x, x) & 0xffffu); }
; __device__ __forceinline__ float bf2f(bf16_t v) { return __uint_as_float((unsigned)v << 16); }
; __device__ __forceinline__ u32x4 pack8(const float* v) { u32x4 w; w.x = cvt_pk_bf16(v[0], v[1]); w.y = cvt_pk_bf16(v[2], v[3]); w.z = cvt_pk_bf16(v[4], v[5]); w.w = cvt_pk_bf16(v[6], v[7]); return w; }
; #define GLA_BAR() do { asm volatile("s_waitcnt lgkmcnt(0)" ::: "memory"); __builtin_amdgcn_s_barrier(); asm volatile("" ::: "memory"); } while (0)
; template <int DK, int DVS, bool RET> ...
;     ...
;                 for (int j = 0; j < 4; ++j) { const int it = tid + 512 * j, p = it & 63, k0 = (it >> 6) * 8; const float bb = (float)(p + 1) * lg;
;                     const float eq = __expf(bb), ek = __expf(-bb); float a[8], c[8];
; #pragma unroll
;                     for (int e = 0; e < 8; ++e) { a[e] = bf2f((bf16_t)qv[j][e]) * eq; c[e] = bf2f((bf16_t)kv[j][e]) * ek; }
;                     *(LAS u32x4*)(QD + p * LK + k0) = pack8(a); *(LAS u32x4*)(KD + p * LK + k0) = pack8(c); }
;             } else {
;                 float c = 0.f;
; #pragma unroll
;                 for (int i = 0; i < PPT; ++i) c += lc[i];
;                 TOT[pg * 128 + kx] = c;
;                 GLA_BAR();
;                 float off = 0.f; bl = 0.f;
; #pragma unroll
;                 for (int g = 0; g < NPG; ++g) { const float t = TOT[g * 128 + kx]; if (g < pg) off += t; bl += t; }
;                 float bb = off;
; #pragma unroll
;                 for (int i = 0; i < PPT; ++i) { const int p = pg * PPT + i;
;                     const float qf = bf2f(qr[i]), kf = 1.f - __expf(lc[i]); bb += lc[i];
;                     QD[p * LK + kx] = f2bf(qf * __expf(bb)); KD[p * LK + kx] = f2bf(kf * __expf(-bb)); }
;             }
;             if (pg == 0) EL[kx] = __expf(bl);
;             { const int p = tid >> 3, vg = tid & 7; *(LAS vvec_t*)(VI + p * LV + vg * VPT) = vraw; }
;         }
;         if (step + 1 < 68) GLA_LOAD(step + 1);
	v_and_b32_e32 v231, 0xffff0000, v16
	v_lshlrev_b32_e32 v230, 16, v16
	v_and_b32_e32 v229, 0xffff0000, v12
	v_lshlrev_b32_e32 v228, 16, v12
	v_pk_mul_f32 v[232:233], v[102:103], v[230:231]
	v_and_b32_e32 v231, 0xffff0000, v13
	v_lshlrev_b32_e32 v230, 16, v13
	v_and_b32_e32 v237, 0xffff0000, v14
	v_lshlrev_b32_e32 v236, 16, v14
	v_and_b32_e32 v241, 0xffff0000, v15
	v_lshlrev_b32_e32 v240, 16, v15
	v_pk_mul_f32 v[228:229], v[100:101], v[228:229]
	v_pk_mul_f32 v[230:231], v[100:101], v[230:231]
	v_and_b32_e32 v235, 0xffff0000, v17
	v_lshlrev_b32_e32 v234, 16, v17
	v_pk_mul_f32 v[236:237], v[100:101], v[236:237]
	v_and_b32_e32 v239, 0xffff0000, v18
	v_lshlrev_b32_e32 v238, 16, v18
	v_pk_mul_f32 v[240:241], v[100:101], v[240:241]
	v_and_b32_e32 v243, 0xffff0000, v19
	v_lshlrev_b32_e32 v242, 16, v19
	v_pk_mul_f32 v[234:235], v[102:103], v[234:235]
	v_pk_mul_f32 v[238:239], v[102:103], v[238:239]
	v_pk_mul_f32 v[242:243], v[102:103], v[242:243]
	v_cvt_pk_bf16_f32 v228, v228, v229
	v_cvt_pk_bf16_f32 v229, v230, v231
	v_cvt_pk_bf16_f32 v230, v236, v237
	v_cvt_pk_bf16_f32 v231, v240, v241
	ds_write_b128 v180, v[228:231]
	v_cvt_pk_bf16_f32 v228, v232, v233
	v_cvt_pk_bf16_f32 v229, v234, v235
	v_cvt_pk_bf16_f32 v230, v238, v239
	v_cvt_pk_bf16_f32 v231, v242, v243
	ds_write_b128 v181, v[228:231]
	s_waitcnt vmcnt(3)
	v_and_b32_e32 v231, 0xffff0000, v24
	v_lshlrev_b32_e32 v230, 16, v24
	v_and_b32_e32 v229, 0xffff0000, v20
	v_lshlrev_b32_e32 v228, 16, v20
	v_pk_mul_f32 v[232:233], v[102:103], v[230:231]
	v_and_b32_e32 v231, 0xffff0000, v21
	v_lshlrev_b32_e32 v230, 16, v21
	v_and_b32_e32 v237, 0xffff0000, v22
	v_lshlrev_b32_e32 v236, 16, v22
	v_and_b32_e32 v241, 0xffff0000, v23
	v_lshlrev_b32_e32 v240, 16, v23
	v_pk_mul_f32 v[228:229], v[100:101], v[228:229]
	v_pk_mul_f32 v[230:231], v[100:101], v[230:231]
	v_and_b32_e32 v235, 0xffff0000, v25
	v_lshlrev_b32_e32 v234, 16, v25
	v_pk_mul_f32 v[236:237], v[100:101], v[236:237]
	v_and_b32_e32 v239, 0xffff0000, v26
	v_lshlrev_b32_e32 v238, 16, v26
	v_pk_mul_f32 v[240:241], v[100:101], v[240:241]
	v_and_b32_e32 v243, 0xffff0000, v27
	v_lshlrev_b32_e32 v242, 16, v27
	v_pk_mul_f32 v[234:235], v[102:103], v[234:235]
	v_pk_mul_f32 v[238:239], v[102:103], v[238:239]
	v_pk_mul_f32 v[242:243], v[102:103], v[242:243]
	v_cvt_pk_bf16_f32 v228, v228, v229
	v_cvt_pk_bf16_f32 v229, v230, v231
	v_cvt_pk_bf16_f32 v230, v236, v237
	v_cvt_pk_bf16_f32 v231, v240, v241
	ds_write_b128 v182, v[228:231]
	v_cvt_pk_bf16_f32 v228, v232, v233
	v_cvt_pk_bf16_f32 v229, v234, v235
	v_cvt_pk_bf16_f32 v230, v238, v239
	v_cvt_pk_bf16_f32 v231, v242, v243
	ds_write_b128 v183, v[228:231]
	s_waitcnt vmcnt(1)
	v_and_b32_e32 v231, 0xffff0000, v32
	v_lshlrev_b32_e32 v230, 16, v32
	v_and_b32_e32 v229, 0xffff0000, v28
	v_lshlrev_b32_e32 v228, 16, v28
	v_pk_mul_f32 v[232:233], v[102:103], v[230:231]
	v_and_b32_e32 v231, 0xffff0000, v29
	v_lshlrev_b32_e32 v230, 16, v29
	v_and_b32_e32 v237, 0xffff0000, v30
	v_lshlrev_b32_e32 v236, 16, v30
	v_and_b32_e32 v241, 0xffff0000, v31
	v_lshlrev_b32_e32 v240, 16, v31
	v_pk_mul_f32 v[228:229], v[100:101], v[228:229]
	v_pk_mul_f32 v[230:231], v[100:101], v[230:231]
	v_and_b32_e32 v235, 0xffff0000, v33
	v_lshlrev_b32_e32 v234, 16, v33
	v_pk_mul_f32 v[236:237], v[100:101], v[236:237]
	v_and_b32_e32 v239, 0xffff0000, v34
	v_lshlrev_b32_e32 v238, 16, v34
	v_pk_mul_f32 v[240:241], v[100:101], v[240:241]
	v_and_b32_e32 v243, 0xffff0000, v35
	v_lshlrev_b32_e32 v242, 16, v35
	v_pk_mul_f32 v[234:235], v[102:103], v[234:235]
	v_pk_mul_f32 v[238:239], v[102:103], v[238:239]
	v_pk_mul_f32 v[242:243], v[102:103], v[242:243]
	v_cvt_pk_bf16_f32 v228, v228, v229
	v_cvt_pk_bf16_f32 v229, v230, v231
	v_cvt_pk_bf16_f32 v230, v236, v237
	v_cvt_pk_bf16_f32 v231, v240, v241
	ds_write_b128 v184, v[228:231]
	v_cvt_pk_bf16_f32 v228, v232, v233
	v_cvt_pk_bf16_f32 v229, v234, v235
	v_cvt_pk_bf16_f32 v230, v238, v239
	v_cvt_pk_bf16_f32 v231, v242, v243
	ds_write_b128 v185, v[228:231]
	s_and_saveexec_b64 s[40:41], vcc
	ds_write_b32 v171, v173
	s_or_b64 exec, exec, s[40:41]
	s_add_i32 s36, s45, 1
	s_cmpk_eq_i32 s42, 0xffbd
	s_waitcnt vmcnt(0)
	ds_write_b128 v172, v[212:215]
	s_cbranch_scc1 .LBB0_70
	s_cmp_gt_u32 s45, 2
	s_cselect_b32 s40, 0x46, 2
	s_add_i32 s45, s40, s42
	s_and_b64 s[40:41], s[22:23], exec
	s_cselect_b32 s40, s36, s45
	s_lshl_b32 s40, s40, 6
	s_ashr_i32 s41, s40, 31
	v_lshl_add_u64 v[4:5], v[94:95], 0, s[40:41]
	v_lshlrev_b64 v[4:5], 11, v[4:5]
	v_lshl_add_u64 v[28:29], s[28:29], 0, v[4:5]
	v_lshl_add_u64 v[30:31], s[24:25], 0, v[4:5]
	v_lshl_add_u64 v[4:5], v[28:29], 0, v[86:87]
	v_lshl_add_u64 v[8:9], v[30:31], 0, v[86:87]
	v_lshl_add_u64 v[12:13], v[28:29], 0, v[88:89]
	v_lshl_add_u64 v[16:17], v[30:31], 0, v[88:89]
	v_lshl_add_u64 v[20:21], v[28:29], 0, v[90:91]
	v_lshl_add_u64 v[24:25], v[30:31], 0, v[90:91]
	v_lshl_add_u64 v[28:29], v[28:29], 0, v[92:93]
	v_lshl_add_u64 v[32:33], v[30:31], 0, v[92:93]
	global_load_dwordx4 v[4:7], v[4:5], off
	s_nop 0
	global_load_dwordx4 v[8:11], v[8:9], off
	s_nop 0
	global_load_dwordx4 v[12:15], v[12:13], off
	s_nop 0
	global_load_dwordx4 v[16:19], v[16:17], off
	s_nop 0
	global_load_dwordx4 v[20:23], v[20:21], off
	s_nop 0
	global_load_dwordx4 v[24:27], v[24:25], off
	s_nop 0
	global_load_dwordx4 v[28:31], v[28:29], off
	s_nop 0
	global_load_dwordx4 v[32:35], v[32:33], off
	s_branch .LBB0_70
